# row-tile counter poll before the attention-out phase also uses two staggered polls
# speedup vs baseline: 1.0141x; 1.0048x over previous
.Lgb0_spin:
	global_load_dword v1, v5, s[10:11] sc1
	s_sleep 10
	global_load_dword v3, v5, s[10:11] sc1
.Lgb0_spin2:
	s_waitcnt vmcnt(1)
	v_readfirstlane_b32 s9, v1
	s_sub_i32 s9, s9, s8
	s_cmp_ge_i32 s9, 0
	s_cbranch_scc1 .Lgb0_done
	s_sleep 10
	global_load_dword v1, v5, s[10:11] sc1
	s_waitcnt vmcnt(1)
	v_readfirstlane_b32 s9, v3
	s_sub_i32 s9, s9, s8
	s_cmp_ge_i32 s9, 0
	s_cbranch_scc1 .Lgb0_done
	s_sleep 10
	global_load_dword v3, v5, s[10:11] sc1
	s_add_i32 s12, s12, 1
	s_cmp_lt_u32 s12, 0x40000
	s_cbranch_scc1 .Lgb0_spin2

.LBB0_1053:
	s_waitcnt lgkmcnt(0)
	s_and_b32 s0, s91, 7
	s_lshl_b32 s0, s0, 3
	s_bfe_u32 s1, s91, 0x30003
	s_add_i32 s0, s0, s1
	v_readlane_b32 s1, v255, 45
	s_lshl_b32 s1, s1, 6
	s_add_i32 s0, s0, s1
	s_lshl_b32 s0, s0, 2
	s_add_i32 s0, s0, 14080
	v_readlane_b32 s2, v251, 32
	v_readlane_b32 s3, v251, 33
	s_add_u32 s2, s2, s0
	s_addc_u32 s3, s3, 0
	s_mov_b32 s12, 0
	v_mov_b32_e32 v5, 0
	global_load_dword v1, v5, s[2:3] sc1
	s_sleep 10
.Lgb7_spin:
	global_load_dword v3, v5, s[2:3] sc1
	s_waitcnt vmcnt(1)
	v_readfirstlane_b32 s9, v1
	s_cmp_ge_u32 s9, 4
	s_cbranch_scc1 .Lgb7_done
	s_sleep 10
	global_load_dword v1, v5, s[2:3] sc1
	s_waitcnt vmcnt(1)
	v_readfirstlane_b32 s9, v3
	s_cmp_ge_u32 s9, 4
	s_cbranch_scc1 .Lgb7_done
	s_sleep 10
	s_add_i32 s12, s12, 1
	s_cmp_lt_u32 s12, 0x80000
	s_cbranch_scc1 .Lgb7_spin
